# both layer-0 tables (U and V) converted inside the phase-3 item loop, two rows per item; phase-3 load hoist renames only registers other blocks touch; phase 4 no longer converts
# speedup vs baseline: 1.0128x; 1.0016x over previous
.LBB0_950:
	s_or_b64 exec, exec, s[2:3]
	v_and_b32_e32 v63, 15, v120
	v_lshlrev_b32_e32 v61, 6, v63
	v_or_b32_e32 v50, v61, v121
	v_lshlrev_b64 v[18:19], 10, v[64:65]
	v_or_b32_e32 v2, v18, v50
	v_mov_b32_e32 v3, v19
	s_mov_b64 s[2:3], 0x400
	v_readlane_b32 s44, v245, 44
	v_lshlrev_b64 v[4:5], 1, v[2:3]
	v_lshl_add_u64 v[14:15], v[2:3], 0, s[2:3]
	v_lshlrev_b32_e32 v1, 2, v50
	v_readlane_b32 s52, v245, 52
	v_readlane_b32 s53, v245, 53
	v_lshl_add_u64 v[8:9], s[64:65], 0, v[4:5]
	v_lshlrev_b64 v[22:23], 1, v[14:15]
	v_readlane_b32 s54, v245, 54
	v_readlane_b32 s55, v245, 55
	v_readlane_b32 s56, v245, 56
	v_readlane_b32 s57, v245, 57
	global_load_dword v21, v1, s[52:53]
	s_nop 1
	global_load_dword v20, v1, s[54:55]
	s_nop 0
	global_load_dword v17, v1, s[56:57]
	v_lshl_add_u64 v[6:7], s[62:63], 0, v[4:5]
	v_lshl_add_u64 v[10:11], s[66:67], 0, v[4:5]
	v_lshl_add_u64 v[4:5], s[68:69], 0, v[4:5]
	v_lshl_add_u64 v[12:13], v[2:3], 2, s[70:71]
	v_lshl_add_u64 v[24:25], s[62:63], 0, v[22:23]
	v_lshl_add_u64 v[26:27], s[64:65], 0, v[22:23]
	v_lshl_add_u64 v[32:33], s[66:67], 0, v[22:23]
	global_load_ushort v101, v[8:9], off
	global_load_ushort v30, v[10:11], off
	global_load_ushort v102, v[4:5], off
	global_load_dword v29, v[12:13], off
	global_load_ushort v1, v[24:25], off
	global_load_ushort v99, v[26:27], off
	global_load_ushort v46, v[32:33], off
	global_load_ushort v16, v[6:7], off
	v_lshl_add_u64 v[8:9], v[2:3], 0, s[76:77]
	s_mov_b64 s[2:3], 0xc00
	v_lshlrev_b64 v[10:11], 1, v[8:9]
	v_lshl_add_u64 v[2:3], v[2:3], 0, s[2:3]
	v_lshl_add_u64 v[4:5], s[68:69], 0, v[22:23]
	v_lshl_add_u64 v[6:7], v[14:15], 2, s[70:71]
	v_lshl_add_u64 v[12:13], s[62:63], 0, v[10:11]
	v_lshl_add_u64 v[14:15], s[64:65], 0, v[10:11]
	v_lshl_add_u64 v[22:23], s[66:67], 0, v[10:11]
	v_lshl_add_u64 v[10:11], s[68:69], 0, v[10:11]
	v_lshlrev_b64 v[24:25], 1, v[2:3]
	v_lshl_add_u64 v[8:9], v[8:9], 2, s[70:71]
	v_lshl_add_u64 v[26:27], s[62:63], 0, v[24:25]
	global_load_ushort v100, v[4:5], off
	global_load_dword v97, v[6:7], off
	global_load_ushort v98, v[14:15], off
	global_load_ushort v94, v[22:23], off
	global_load_ushort v47, v[10:11], off
	global_load_dword v93, v[8:9], off
	s_nop 0
	global_load_ushort v10, v[26:27], off
	global_load_ushort v11, v[12:13], off
	v_lshl_add_u64 v[4:5], s[64:65], 0, v[24:25]
	v_lshl_add_u64 v[6:7], s[66:67], 0, v[24:25]
	v_lshl_add_u64 v[8:9], s[68:69], 0, v[24:25]
	v_lshl_add_u64 v[2:3], v[2:3], 2, s[70:71]
	global_load_ushort v96, v[4:5], off
	global_load_ushort v88, v[6:7], off
	global_load_ushort v95, v[8:9], off
	global_load_dword v90, v[2:3], off
	v_readlane_b32 s45, v245, 45
	v_readlane_b32 s46, v245, 46
	v_readlane_b32 s47, v245, 47
	v_readlane_b32 s48, v245, 48
	v_readlane_b32 s49, v245, 49
	v_readlane_b32 s50, v245, 50
	v_readlane_b32 s51, v245, 51
	v_readlane_b32 s58, v245, 58
	v_readlane_b32 s59, v245, 59
	s_waitcnt vmcnt(15)
	v_lshlrev_b32_e32 v1, 16, v1
	s_waitcnt vmcnt(12)
	v_lshlrev_b32_e32 v16, 16, v16
	s_waitcnt vmcnt(5)
	v_lshlrev_b32_e32 v3, 16, v10
	s_waitcnt vmcnt(4)
	v_lshlrev_b32_e32 v2, 16, v11
	s_and_saveexec_b64 s[2:3], s[82:83]
	s_xor_b64 s[2:3], exec, s[2:3]
	v_mov_b32_e32 v4, s86
	s_or_saveexec_b64 s[2:3], s[2:3]
	v_mov_b32_e32 v84, 0
	v_mov_b32_e32 v86, 0
	v_lshl_add_u64 v[18:19], v[18:19], 0, v[50:51]
	v_mov_b32_e32 v87, 0
	v_mov_b32_e32 v92, 0
	s_xor_b64 exec, exec, s[2:3]
	s_cbranch_execz .LBB0_954
	s_mov_b64 s[44:45], 0x1000
	v_lshl_add_u64 v[22:23], v[18:19], 0, s[44:45]
	v_lshlrev_b64 v[24:25], 1, v[22:23]
	v_lshl_add_u64 v[26:27], s[62:63], 0, v[24:25]
	v_lshl_add_u64 v[32:33], s[64:65], 0, v[24:25]
	v_lshl_add_u64 v[34:35], s[66:67], 0, v[24:25]
	v_lshl_add_u64 v[24:25], s[68:69], 0, v[24:25]
	v_lshl_add_u64 v[22:23], v[22:23], 2, s[70:71]
	global_load_ushort v4, v[26:27], off
	s_nop 0
	global_load_ushort v176, v[34:35], off
	s_nop 0
	global_load_ushort v177, v[24:25], off
	s_nop 0
	global_load_dword v86, v[22:23], off
	s_nop 0
	global_load_ushort v178, v[32:33], off
.LBB0_954:
	s_or_b64 exec, exec, s[2:3]
	s_and_saveexec_b64 s[2:3], s[82:83]
	s_xor_b64 s[2:3], exec, s[2:3]
	v_mov_b32_e32 v5, s86
	s_or_saveexec_b64 s[2:3], s[2:3]
	v_mov_b32_e32 v80, 0
	v_mov_b32_e32 v82, 0
	v_mov_b32_e32 v83, 0
	v_mov_b32_e32 v91, 0
	s_xor_b64 exec, exec, s[2:3]
	s_cbranch_execz .LBB0_958
	s_mov_b64 s[48:49], 0x1400
	v_lshl_add_u64 v[22:23], v[18:19], 0, s[48:49]
	v_lshlrev_b64 v[24:25], 1, v[22:23]
	v_lshl_add_u64 v[26:27], s[62:63], 0, v[24:25]
	v_lshl_add_u64 v[32:33], s[64:65], 0, v[24:25]
	v_lshl_add_u64 v[34:35], s[66:67], 0, v[24:25]
	v_lshl_add_u64 v[24:25], s[68:69], 0, v[24:25]
	v_lshl_add_u64 v[22:23], v[22:23], 2, s[70:71]
	global_load_ushort v5, v[26:27], off
	s_nop 0
	global_load_ushort v179, v[34:35], off
	s_nop 0
	global_load_ushort v180, v[24:25], off
	s_nop 0
	global_load_dword v82, v[22:23], off
	s_nop 0
	global_load_ushort v181, v[32:33], off
.LBB0_958:
	s_or_b64 exec, exec, s[2:3]
	s_and_saveexec_b64 s[2:3], s[82:83]
	s_xor_b64 s[2:3], exec, s[2:3]
	v_mov_b32_e32 v6, s86
	s_or_saveexec_b64 s[2:3], s[2:3]
	v_mov_b32_e32 v76, 0
	v_mov_b32_e32 v78, 0
	v_mov_b32_e32 v79, 0
	v_mov_b32_e32 v89, 0
	s_xor_b64 exec, exec, s[2:3]
	s_cbranch_execz .LBB0_962
	s_mov_b64 s[44:45], 0x1800
	v_lshl_add_u64 v[22:23], v[18:19], 0, s[44:45]
	v_lshlrev_b64 v[24:25], 1, v[22:23]
	v_lshl_add_u64 v[26:27], s[62:63], 0, v[24:25]
	v_lshl_add_u64 v[32:33], s[64:65], 0, v[24:25]
	v_lshl_add_u64 v[34:35], s[66:67], 0, v[24:25]
	v_lshl_add_u64 v[24:25], s[68:69], 0, v[24:25]
	v_lshl_add_u64 v[22:23], v[22:23], 2, s[70:71]
	global_load_ushort v6, v[26:27], off
	s_nop 0
	global_load_ushort v182, v[34:35], off
	s_nop 0
	global_load_ushort v183, v[24:25], off
	s_nop 0
	global_load_dword v78, v[22:23], off
	s_nop 0
	global_load_ushort v184, v[32:33], off
.LBB0_962:
	s_or_b64 exec, exec, s[2:3]
	s_and_saveexec_b64 s[2:3], s[82:83]
	s_xor_b64 s[2:3], exec, s[2:3]
	v_mov_b32_e32 v7, s86
	s_or_saveexec_b64 s[2:3], s[2:3]
	v_mov_b32_e32 v72, 0
	v_mov_b32_e32 v74, 0
	v_mov_b32_e32 v75, 0
	v_mov_b32_e32 v85, 0
	s_xor_b64 exec, exec, s[2:3]
	s_cbranch_execz .LBB0_966
	s_mov_b64 s[48:49], 0x1c00
	v_lshl_add_u64 v[22:23], v[18:19], 0, s[48:49]
	v_lshlrev_b64 v[24:25], 1, v[22:23]
	v_lshl_add_u64 v[26:27], s[62:63], 0, v[24:25]
	v_lshl_add_u64 v[32:33], s[64:65], 0, v[24:25]
	v_lshl_add_u64 v[34:35], s[66:67], 0, v[24:25]
	v_lshl_add_u64 v[24:25], s[68:69], 0, v[24:25]
	v_lshl_add_u64 v[22:23], v[22:23], 2, s[70:71]
	global_load_ushort v7, v[26:27], off
	s_nop 0
	global_load_ushort v185, v[34:35], off
	s_nop 0
	global_load_ushort v186, v[24:25], off
	s_nop 0
	global_load_dword v74, v[22:23], off
	s_nop 0
	global_load_ushort v187, v[32:33], off
.LBB0_966:
	s_or_b64 exec, exec, s[2:3]
	s_and_saveexec_b64 s[2:3], s[82:83]
	s_xor_b64 s[2:3], exec, s[2:3]
	v_mov_b32_e32 v8, s86
	s_or_saveexec_b64 s[2:3], s[2:3]
	v_mov_b32_e32 v68, 0
	v_mov_b32_e32 v69, 0
	v_mov_b32_e32 v70, 0
	v_mov_b32_e32 v81, 0
	s_xor_b64 exec, exec, s[2:3]
	s_cbranch_execz .LBB0_970
	s_mov_b64 s[44:45], 0x2000
	v_lshl_add_u64 v[22:23], v[18:19], 0, s[44:45]
	v_lshlrev_b64 v[24:25], 1, v[22:23]
	v_lshl_add_u64 v[26:27], s[62:63], 0, v[24:25]
	v_lshl_add_u64 v[32:33], s[64:65], 0, v[24:25]
	v_lshl_add_u64 v[34:35], s[66:67], 0, v[24:25]
	v_lshl_add_u64 v[24:25], s[68:69], 0, v[24:25]
	v_lshl_add_u64 v[22:23], v[22:23], 2, s[70:71]
	global_load_ushort v8, v[26:27], off
	s_nop 0
	global_load_ushort v188, v[34:35], off
	s_nop 0
	global_load_ushort v189, v[24:25], off
	s_nop 0
	global_load_dword v69, v[22:23], off
	s_nop 0
	global_load_ushort v190, v[32:33], off
.LBB0_970:
	s_or_b64 exec, exec, s[2:3]
	s_and_saveexec_b64 s[2:3], s[82:83]
	s_xor_b64 s[2:3], exec, s[2:3]
	v_mov_b32_e32 v9, s86
	s_or_saveexec_b64 s[2:3], s[2:3]
	v_mov_b32_e32 v45, 0
	v_mov_b32_e32 v48, 0
	v_mov_b32_e32 v49, 0
	v_mov_b32_e32 v77, 0
	s_xor_b64 exec, exec, s[2:3]
	s_cbranch_execz .LBB0_974
	s_mov_b64 s[48:49], 0x2400
	v_lshl_add_u64 v[22:23], v[18:19], 0, s[48:49]
	v_lshlrev_b64 v[24:25], 1, v[22:23]
	v_lshl_add_u64 v[26:27], s[62:63], 0, v[24:25]
	v_lshl_add_u64 v[32:33], s[64:65], 0, v[24:25]
	v_lshl_add_u64 v[34:35], s[66:67], 0, v[24:25]
	v_lshl_add_u64 v[24:25], s[68:69], 0, v[24:25]
	v_lshl_add_u64 v[22:23], v[22:23], 2, s[70:71]
	global_load_ushort v9, v[26:27], off
	s_nop 0
	global_load_ushort v191, v[34:35], off
	s_nop 0
	global_load_ushort v192, v[24:25], off
	s_nop 0
	global_load_dword v48, v[22:23], off
	s_nop 0
	global_load_ushort v193, v[32:33], off
	s_waitcnt vmcnt(30)
.LBB0_974:
	s_or_b64 exec, exec, s[2:3]
	s_and_saveexec_b64 s[2:3], s[82:83]
	s_xor_b64 s[2:3], exec, s[2:3]
	v_mov_b32_e32 v10, s86
	s_or_saveexec_b64 s[2:3], s[2:3]
	v_mov_b32_e32 v40, 0
	v_mov_b32_e32 v42, 0
	v_mov_b32_e32 v43, 0
	v_mov_b32_e32 v73, 0
	s_xor_b64 exec, exec, s[2:3]
	s_cbranch_execz .LBB0_978
	s_mov_b64 s[48:49], 0x2800
	v_lshl_add_u64 v[22:23], v[18:19], 0, s[48:49]
	v_lshlrev_b64 v[24:25], 1, v[22:23]
	v_lshl_add_u64 v[26:27], s[62:63], 0, v[24:25]
	v_lshl_add_u64 v[32:33], s[64:65], 0, v[24:25]
	v_lshl_add_u64 v[34:35], s[66:67], 0, v[24:25]
	v_lshl_add_u64 v[24:25], s[68:69], 0, v[24:25]
	v_lshl_add_u64 v[22:23], v[22:23], 2, s[70:71]
	global_load_ushort v10, v[26:27], off
	s_nop 0
	global_load_ushort v194, v[34:35], off
	s_nop 0
	global_load_ushort v195, v[24:25], off
	s_nop 0
	global_load_dword v42, v[22:23], off
	s_nop 0
	global_load_ushort v196, v[32:33], off
.LBB0_978:
	s_or_b64 exec, exec, s[2:3]
	s_and_saveexec_b64 s[2:3], s[82:83]
	s_xor_b64 s[2:3], exec, s[2:3]
	v_mov_b32_e32 v11, s86
	s_or_saveexec_b64 s[2:3], s[2:3]
	v_mov_b32_e32 v37, 0
	v_mov_b32_e32 v39, 0
	v_mov_b32_e32 v41, 0
	v_mov_b32_e32 v71, 0
	s_xor_b64 exec, exec, s[2:3]
	s_cbranch_execz .LBB0_982
	s_mov_b64 s[48:49], 0x2c00
	v_lshl_add_u64 v[22:23], v[18:19], 0, s[48:49]
	v_lshlrev_b64 v[24:25], 1, v[22:23]
	v_lshl_add_u64 v[26:27], s[62:63], 0, v[24:25]
	v_lshl_add_u64 v[32:33], s[66:67], 0, v[24:25]
	global_load_ushort v11, v[26:27], off
	global_load_ushort v197, v[32:33], off
	v_lshl_add_u64 v[26:27], s[64:65], 0, v[24:25]
	v_lshl_add_u64 v[24:25], s[68:69], 0, v[24:25]
	global_load_ushort v198, v[24:25], off
	s_nop 0
	global_load_ushort v199, v[26:27], off
	v_lshl_add_u64 v[22:23], v[22:23], 2, s[70:71]
	global_load_dword v39, v[22:23], off
.LBB0_982:
	s_or_b64 exec, exec, s[2:3]
	s_and_saveexec_b64 s[2:3], s[82:83]
	s_xor_b64 s[2:3], exec, s[2:3]
	v_mov_b32_e32 v12, s86
	s_or_saveexec_b64 s[2:3], s[2:3]
	v_mov_b32_e32 v33, 0
	v_mov_b32_e32 v35, 0
	v_mov_b32_e32 v36, 0
	v_mov_b32_e32 v67, 0
	s_xor_b64 exec, exec, s[2:3]
	s_cbranch_execz .LBB0_986
	s_mov_b64 s[48:49], 0x3000
	v_lshl_add_u64 v[22:23], v[18:19], 0, s[48:49]
	v_lshlrev_b64 v[24:25], 1, v[22:23]
	v_lshl_add_u64 v[26:27], s[62:63], 0, v[24:25]
	v_lshl_add_u64 v[32:33], s[64:65], 0, v[24:25]
	v_lshl_add_u64 v[34:35], s[66:67], 0, v[24:25]
	v_lshl_add_u64 v[24:25], s[68:69], 0, v[24:25]
	v_lshl_add_u64 v[22:23], v[22:23], 2, s[70:71]
	global_load_ushort v12, v[26:27], off
	s_nop 0
	global_load_ushort v200, v[34:35], off
	s_nop 0
	global_load_ushort v201, v[24:25], off
	s_nop 0
	global_load_dword v202, v[22:23], off
	s_nop 0
	global_load_ushort v203, v[32:33], off
.LBB0_986:
	s_or_b64 exec, exec, s[2:3]
	s_and_saveexec_b64 s[2:3], s[82:83]
	s_xor_b64 s[2:3], exec, s[2:3]
	v_mov_b32_e32 v13, s86
	s_or_saveexec_b64 s[2:3], s[2:3]
	v_mov_b32_e32 v28, 0
	v_mov_b32_e32 v31, 0
	v_mov_b32_e32 v32, 0
	v_mov_b32_e32 v44, 0
	s_xor_b64 exec, exec, s[2:3]
	s_cbranch_execz .LBB0_990
	s_mov_b64 s[48:49], 0x3400
	v_lshl_add_u64 v[22:23], v[18:19], 0, s[48:49]
	v_lshlrev_b64 v[24:25], 1, v[22:23]
	v_lshl_add_u64 v[26:27], s[62:63], 0, v[24:25]
	v_lshl_add_u64 v[104:105], s[64:65], 0, v[24:25]
	v_lshl_add_u64 v[106:107], s[66:67], 0, v[24:25]
	v_lshl_add_u64 v[24:25], s[68:69], 0, v[24:25]
	v_lshl_add_u64 v[22:23], v[22:23], 2, s[70:71]
	global_load_ushort v13, v[26:27], off
	s_nop 0
	global_load_ushort v204, v[106:107], off
	s_nop 0
	global_load_ushort v205, v[24:25], off
	s_nop 0
	global_load_dword v31, v[22:23], off
	s_nop 0
	global_load_ushort v206, v[104:105], off
.LBB0_990:
	s_or_b64 exec, exec, s[2:3]
	s_and_saveexec_b64 s[2:3], s[82:83]
	s_xor_b64 s[2:3], exec, s[2:3]
	v_mov_b32_e32 v14, s86
	s_or_saveexec_b64 s[2:3], s[2:3]
	v_mov_b32_e32 v25, 0
	v_mov_b32_e32 v26, 0
	v_mov_b32_e32 v27, 0
	v_mov_b32_e32 v38, 0
	s_xor_b64 exec, exec, s[2:3]
	s_cbranch_execz .LBB0_994
	s_mov_b64 s[48:49], 0x3800
	v_lshl_add_u64 v[22:23], v[18:19], 0, s[48:49]
	v_lshlrev_b64 v[24:25], 1, v[22:23]
	v_lshl_add_u64 v[26:27], s[62:63], 0, v[24:25]
	v_lshl_add_u64 v[104:105], s[64:65], 0, v[24:25]
	v_lshl_add_u64 v[106:107], s[66:67], 0, v[24:25]
	v_lshl_add_u64 v[24:25], s[68:69], 0, v[24:25]
	v_lshl_add_u64 v[22:23], v[22:23], 2, s[70:71]
	global_load_ushort v14, v[26:27], off
	s_nop 0
	global_load_ushort v207, v[106:107], off
	s_nop 0
	global_load_ushort v208, v[24:25], off
	s_nop 0
	global_load_dword v209, v[22:23], off
	s_nop 0
	global_load_ushort v210, v[104:105], off
.LBB0_994:
	s_or_b64 exec, exec, s[2:3]
	s_and_saveexec_b64 s[2:3], s[82:83]
	s_xor_b64 s[2:3], exec, s[2:3]
	v_mov_b32_e32 v15, s86
	s_or_saveexec_b64 s[2:3], s[2:3]
	v_mov_b32_e32 v22, 0
	v_mov_b32_e32 v23, 0
	v_mov_b32_e32 v24, 0
	v_mov_b32_e32 v34, 0
	s_xor_b64 exec, exec, s[2:3]
	s_cbranch_execz .LBB0_998
	s_mov_b64 s[48:49], 0x3c00
	v_lshl_add_u64 v[18:19], v[18:19], 0, s[48:49]
	v_lshlrev_b64 v[22:23], 1, v[18:19]
	v_lshl_add_u64 v[104:105], s[62:63], 0, v[22:23]
	v_lshl_add_u64 v[106:107], s[64:65], 0, v[22:23]
	v_lshl_add_u64 v[108:109], s[66:67], 0, v[22:23]
	v_lshl_add_u64 v[22:23], s[68:69], 0, v[22:23]
	v_lshl_add_u64 v[18:19], v[18:19], 2, s[70:71]
	global_load_ushort v15, v[104:105], off
	global_load_ushort v211, v[108:109], off
	s_nop 0
	global_load_ushort v212, v[22:23], off
	s_nop 0
	global_load_dword v213, v[18:19], off
	s_nop 0
	global_load_ushort v214, v[106:107], off
.LBB0_998:
	s_or_b64 exec, exec, s[2:3]
	s_waitcnt vmcnt(0)
	s_mov_b64 s[2:3], exec
	s_andn2_b64 exec, exec, s[82:83]
	v_lshlrev_b32_e32 v4, 16, v4
	v_lshlrev_b32_e32 v23, 16, v176
	v_lshlrev_b32_e32 v87, 16, v177
	v_cvt_pk_bf16_f32 v84, v23, s0
	v_lshlrev_b32_e32 v92, 16, v178
	v_mov_b32_e32 v26, v176
	v_mov_b32_e32 v24, v177
	v_mov_b32_e32 v22, v178
	v_lshlrev_b32_e32 v5, 16, v5
	v_lshlrev_b32_e32 v23, 16, v179
	v_lshlrev_b32_e32 v83, 16, v180
	v_cvt_pk_bf16_f32 v80, v23, s0
	v_lshlrev_b32_e32 v91, 16, v181
	v_mov_b32_e32 v26, v179
	v_mov_b32_e32 v24, v180
	v_mov_b32_e32 v22, v181
	v_lshlrev_b32_e32 v6, 16, v6
	v_lshlrev_b32_e32 v23, 16, v182
	v_lshlrev_b32_e32 v79, 16, v183
	v_cvt_pk_bf16_f32 v76, v23, s0
	v_lshlrev_b32_e32 v89, 16, v184
	v_mov_b32_e32 v26, v182
	v_mov_b32_e32 v24, v183
	v_mov_b32_e32 v22, v184
	v_lshlrev_b32_e32 v7, 16, v7
	v_lshlrev_b32_e32 v23, 16, v185
	v_lshlrev_b32_e32 v75, 16, v186
	v_cvt_pk_bf16_f32 v72, v23, s0
	v_lshlrev_b32_e32 v85, 16, v187
	v_mov_b32_e32 v26, v185
	v_mov_b32_e32 v24, v186
	v_mov_b32_e32 v22, v187
	v_lshlrev_b32_e32 v8, 16, v8
	v_lshlrev_b32_e32 v23, 16, v188
	v_lshlrev_b32_e32 v70, 16, v189
	v_cvt_pk_bf16_f32 v68, v23, s0
	v_lshlrev_b32_e32 v81, 16, v190
	v_mov_b32_e32 v26, v188
	v_mov_b32_e32 v24, v189
	v_mov_b32_e32 v22, v190
	v_lshlrev_b32_e32 v9, 16, v9
	v_lshlrev_b32_e32 v23, 16, v191
	v_lshlrev_b32_e32 v49, 16, v192
	v_cvt_pk_bf16_f32 v45, v23, s0
	v_lshlrev_b32_e32 v77, 16, v193
	v_mov_b32_e32 v26, v191
	v_mov_b32_e32 v24, v192
	v_mov_b32_e32 v22, v193
	v_lshlrev_b32_e32 v10, 16, v10
	v_lshlrev_b32_e32 v23, 16, v194
	v_lshlrev_b32_e32 v43, 16, v195
	v_cvt_pk_bf16_f32 v40, v23, s0
	v_lshlrev_b32_e32 v73, 16, v196
	v_mov_b32_e32 v26, v194
	v_mov_b32_e32 v24, v195
	v_mov_b32_e32 v22, v196
	v_lshlrev_b32_e32 v11, 16, v11
	v_lshlrev_b32_e32 v22, 16, v197
	v_cvt_pk_bf16_f32 v37, v22, s0
	v_lshlrev_b32_e32 v41, 16, v198
	v_lshlrev_b32_e32 v71, 16, v199
	v_mov_b32_e32 v28, v197
	v_mov_b32_e32 v24, v198
	v_mov_b32_e32 v25, v199
	v_lshlrev_b32_e32 v12, 16, v12
	v_lshlrev_b32_e32 v23, 16, v200
	v_lshlrev_b32_e32 v36, 16, v201
	v_cvt_pk_bf16_f32 v33, v23, s0
	v_lshlrev_b32_e32 v67, 16, v203
	v_mov_b32_e32 v26, v200
	v_mov_b32_e32 v24, v201
	v_mov_b32_e32 v35, v202
	v_mov_b32_e32 v22, v203
	v_lshlrev_b32_e32 v13, 16, v13
	v_lshlrev_b32_e32 v23, 16, v204
	v_lshlrev_b32_e32 v32, 16, v205
	v_cvt_pk_bf16_f32 v28, v23, s0
	v_lshlrev_b32_e32 v44, 16, v206
	v_mov_b32_e32 v26, v204
	v_mov_b32_e32 v24, v205
	v_mov_b32_e32 v22, v206
	v_lshlrev_b32_e32 v14, 16, v14
	v_lshlrev_b32_e32 v23, 16, v207
	v_lshlrev_b32_e32 v27, 16, v208
	v_cvt_pk_bf16_f32 v25, v23, s0
	v_lshlrev_b32_e32 v38, 16, v210
	v_mov_b32_e32 v24, v208
	v_mov_b32_e32 v26, v209
	v_mov_b32_e32 v22, v210
	v_lshlrev_b32_e32 v15, 16, v15
	v_lshlrev_b32_e32 v19, 16, v211
	v_lshlrev_b32_e32 v24, 16, v212
	v_cvt_pk_bf16_f32 v22, v19, s0
	v_lshlrev_b32_e32 v34, 16, v214
	v_mov_b32_e32 v23, v213
	v_mov_b32_e32 v18, v214
	s_mov_b64 exec, s[2:3]
	v_and_b32_e32 v254, 63, v0
	v_lshlrev_b32_e32 v255, 3, v254
	v_lshlrev_b32_e32 v254, 6, v254
	v_readfirstlane_b32 s94, v120
	s_nop 1
	s_sub_u32 s32, s94, 0x800
	s_cmp_lt_u32 s32, 0x4000
	s_cbranch_scc0 .Lp3tab_noconv
	v_max_f32_e64 v176, |v236|, |v237|
	v_max3_f32 v176, |v238|, |v239|, v176
	v_max3_f32 v176, |v240|, |v241|, v176
	v_max3_f32 v176, |v242|, |v243|, v176
	v_max3_f32 v176, |v246|, |v247|, v176
	v_max3_f32 v176, |v248|, |v249|, v176
	v_max3_f32 v176, |v250|, |v251|, v176
	v_max3_f32 v176, |v252|, |v253|, v176
	s_nop 1
	v_mov_b32_dpp v177, v176 quad_perm:[1,0,3,2] row_mask:0xf bank_mask:0xf bound_ctrl:1
	v_max_f32_e32 v177, v177, v177
	v_max_f32_e32 v176, v176, v177
	s_nop 1
	v_mov_b32_dpp v177, v176 quad_perm:[2,3,0,1] row_mask:0xf bank_mask:0xf bound_ctrl:1
	v_max_f32_e32 v177, v177, v177
	v_max_f32_e32 v176, v176, v177
	s_nop 1
	v_mov_b32_dpp v177, v176 row_half_mirror row_mask:0xf bank_mask:0xf bound_ctrl:1
	v_max_f32_e32 v177, v177, v177
	v_max_f32_e32 v176, v176, v177
	s_nop 1
	v_mov_b32_dpp v177, v176 row_mirror row_mask:0xf bank_mask:0xf bound_ctrl:1
	v_max_f32_e32 v177, v177, v177
	v_max_f32_e32 v176, v176, v177
	s_nop 0
	v_readlane_b32 s98, v176, 32
	v_readlane_b32 s99, v176, 48
	v_readlane_b32 s100, v176, 0
	v_readlane_b32 s101, v176, 16
	s_nop 1
	v_max_f32_e64 v176, s99, s99
	v_max_f32_e64 v177, s98, s98
	v_mov_b32_e32 v182, s101
	v_max_f32_e32 v176, v177, v176
	v_max3_f32 v176, s100, v182, v176
	v_mov_b32_e32 v188, 0x40c00000
	v_div_scale_f32 v179, s[98:99], v176, v176, v188
	v_rcp_f32_e32 v180, v179
	v_div_scale_f32 v181, vcc, v188, v176, v188
	v_fma_f32 v182, -v179, v180, 1.0
	v_fmac_f32_e32 v180, v182, v180
	v_mul_f32_e32 v183, v181, v180
	v_fma_f32 v182, -v179, v183, v181
	v_fmac_f32_e32 v183, v182, v180
	v_fma_f32 v182, -v179, v183, v181
	v_div_fmas_f32 v178, v182, v180, v183
	v_div_fixup_f32 v178, v178, v176, v188
	v_cmp_lt_f32_e32 vcc, 0, v176
	v_mov_b32_e32 v186, 0
	v_mov_b32_e32 v187, 0
	v_cndmask_b32_e32 v178, 0, v178, vcc
	v_mul_f32_e32 v184, 0x3e2aaaab, v176
	v_mul_f32_e32 v236, v236, v178
	v_mul_f32_e32 v237, v237, v178
	v_mul_f32_e32 v238, v238, v178
	v_mul_f32_e32 v239, v239, v178
	v_mul_f32_e32 v240, v240, v178
	v_mul_f32_e32 v241, v241, v178
	v_mul_f32_e32 v242, v242, v178
	v_mul_f32_e32 v243, v243, v178
	v_mul_f32_e32 v246, v246, v178
	v_mul_f32_e32 v247, v247, v178
	v_mul_f32_e32 v248, v248, v178
	v_mul_f32_e32 v249, v249, v178
	v_mul_f32_e32 v250, v250, v178
	v_mul_f32_e32 v251, v251, v178
	v_mul_f32_e32 v252, v252, v178
	v_mul_f32_e32 v253, v253, v178
	v_cvt_scalef32_pk_fp4_f32 v186, v236, v237, 1.0
	v_cvt_scalef32_pk_fp4_f32 v187, v246, v247, 1.0
	v_cvt_scalef32_pk_fp4_f32 v186, v238, v239, 1.0 op_sel:[0,0,1,0]
	v_cvt_scalef32_pk_fp4_f32 v187, v248, v249, 1.0 op_sel:[0,0,1,0]
	v_cvt_scalef32_pk_fp4_f32 v186, v240, v241, 1.0 op_sel:[0,0,0,1]
	v_cvt_scalef32_pk_fp4_f32 v187, v250, v251, 1.0 op_sel:[0,0,0,1]
	v_cvt_scalef32_pk_fp4_f32 v186, v242, v243, 1.0 op_sel:[0,0,1,1]
	v_cvt_scalef32_pk_fp4_f32 v187, v252, v253, 1.0 op_sel:[0,0,1,1]
	v_mov_b32_e32 v185, 0
	v_readlane_b32 s100, v244, 28
	v_readlane_b32 s101, v244, 29
	s_lshl_b32 s94, s32, 9
	s_nop 0
	s_add_u32 s100, s100, 0x4280000
	s_addc_u32 s101, s101, 0
	s_add_u32 s94, s100, s94
	s_addc_u32 s95, s101, 0
	global_store_dwordx2 v255, v[186:187], s[94:95]
	s_lshl_b32 s94, s32, 2
	s_add_u32 s100, s100, 0x6090800
	s_addc_u32 s101, s101, 0
	s_add_u32 s94, s100, s94
	s_addc_u32 s95, s101, 0
	s_mov_b64 s[98:99], exec
	s_mov_b64 exec, 1
	global_store_dword v185, v184, s[94:95]
	s_mov_b64 exec, s[98:99]
	s_add_u32 s32, s32, 0x4000
	v_max_f32_e64 v176, |v216|, |v217|
	v_max3_f32 v176, |v218|, |v219|, v176
	v_max3_f32 v176, |v220|, |v221|, v176
	v_max3_f32 v176, |v222|, |v223|, v176
	v_max3_f32 v176, |v224|, |v225|, v176
	v_max3_f32 v176, |v226|, |v227|, v176
	v_max3_f32 v176, |v228|, |v229|, v176
	v_max3_f32 v176, |v230|, |v231|, v176
	s_nop 1
	v_mov_b32_dpp v177, v176 quad_perm:[1,0,3,2] row_mask:0xf bank_mask:0xf bound_ctrl:1
	v_max_f32_e32 v177, v177, v177
	v_max_f32_e32 v176, v176, v177
	s_nop 1
	v_mov_b32_dpp v177, v176 quad_perm:[2,3,0,1] row_mask:0xf bank_mask:0xf bound_ctrl:1
	v_max_f32_e32 v177, v177, v177
	v_max_f32_e32 v176, v176, v177
	s_nop 1
	v_mov_b32_dpp v177, v176 row_half_mirror row_mask:0xf bank_mask:0xf bound_ctrl:1
	v_max_f32_e32 v177, v177, v177
	v_max_f32_e32 v176, v176, v177
	s_nop 1
	v_mov_b32_dpp v177, v176 row_mirror row_mask:0xf bank_mask:0xf bound_ctrl:1
	v_max_f32_e32 v177, v177, v177
	v_max_f32_e32 v176, v176, v177
	s_nop 0
	v_readlane_b32 s98, v176, 32
	v_readlane_b32 s99, v176, 48
	v_readlane_b32 s100, v176, 0
	v_readlane_b32 s101, v176, 16
	s_nop 1
	v_max_f32_e64 v176, s99, s99
	v_max_f32_e64 v177, s98, s98
	v_mov_b32_e32 v182, s101
	v_max_f32_e32 v176, v177, v176
	v_max3_f32 v176, s100, v182, v176
	v_mov_b32_e32 v188, 0x40c00000
	v_div_scale_f32 v179, s[98:99], v176, v176, v188
	v_rcp_f32_e32 v180, v179
	v_div_scale_f32 v181, vcc, v188, v176, v188
	v_fma_f32 v182, -v179, v180, 1.0
	v_fmac_f32_e32 v180, v182, v180
	v_mul_f32_e32 v183, v181, v180
	v_fma_f32 v182, -v179, v183, v181
	v_fmac_f32_e32 v183, v182, v180
	v_fma_f32 v182, -v179, v183, v181
	v_div_fmas_f32 v178, v182, v180, v183
	v_div_fixup_f32 v178, v178, v176, v188
	v_cmp_lt_f32_e32 vcc, 0, v176
	v_mov_b32_e32 v186, 0
	v_mov_b32_e32 v187, 0
	v_cndmask_b32_e32 v178, 0, v178, vcc
	v_mul_f32_e32 v184, 0x3e2aaaab, v176
	v_mul_f32_e32 v216, v216, v178
	v_mul_f32_e32 v217, v217, v178
	v_mul_f32_e32 v218, v218, v178
	v_mul_f32_e32 v219, v219, v178
	v_mul_f32_e32 v220, v220, v178
	v_mul_f32_e32 v221, v221, v178
	v_mul_f32_e32 v222, v222, v178
	v_mul_f32_e32 v223, v223, v178
	v_mul_f32_e32 v224, v224, v178
	v_mul_f32_e32 v225, v225, v178
	v_mul_f32_e32 v226, v226, v178
	v_mul_f32_e32 v227, v227, v178
	v_mul_f32_e32 v228, v228, v178
	v_mul_f32_e32 v229, v229, v178
	v_mul_f32_e32 v230, v230, v178
	v_mul_f32_e32 v231, v231, v178
	v_cvt_scalef32_pk_fp4_f32 v186, v216, v217, 1.0
	v_cvt_scalef32_pk_fp4_f32 v187, v224, v225, 1.0
	v_cvt_scalef32_pk_fp4_f32 v186, v218, v219, 1.0 op_sel:[0,0,1,0]
	v_cvt_scalef32_pk_fp4_f32 v187, v226, v227, 1.0 op_sel:[0,0,1,0]
	v_cvt_scalef32_pk_fp4_f32 v186, v220, v221, 1.0 op_sel:[0,0,0,1]
	v_cvt_scalef32_pk_fp4_f32 v187, v228, v229, 1.0 op_sel:[0,0,0,1]
	v_cvt_scalef32_pk_fp4_f32 v186, v222, v223, 1.0 op_sel:[0,0,1,1]
	v_cvt_scalef32_pk_fp4_f32 v187, v230, v231, 1.0 op_sel:[0,0,1,1]
	v_mov_b32_e32 v185, 0
	v_readlane_b32 s100, v244, 28
	v_readlane_b32 s101, v244, 29
	s_lshl_b32 s94, s32, 9
	s_nop 0
	s_add_u32 s100, s100, 0x4280000
	s_addc_u32 s101, s101, 0
	s_add_u32 s94, s100, s94
	s_addc_u32 s95, s101, 0
	global_store_dwordx2 v255, v[186:187], s[94:95]
	s_lshl_b32 s94, s32, 2
	s_add_u32 s100, s100, 0x6090800
	s_addc_u32 s101, s101, 0
	s_add_u32 s94, s100, s94
	s_addc_u32 s95, s101, 0
	s_mov_b64 s[98:99], exec
	s_mov_b64 exec, 1
	global_store_dword v185, v184, s[94:95]
	s_mov_b64 exec, s[98:99]
.Lp3tab_noconv:
	v_readfirstlane_b32 s94, v120
	s_nop 1
	s_cmp_lt_u32 s94, 0x4000
	s_cbranch_scc0 .Lp3tab_noload
	s_lshl_b32 s32, s94, 12
	v_readlane_b32 s98, v244, 22
	v_readlane_b32 s99, v244, 23
	s_nop 1
	s_add_u32 s94, s98, s32
	s_addc_u32 s95, s99, 0
	global_load_dwordx4 v[236:239], v254, s[94:95] nt
	global_load_dwordx4 v[240:243], v254, s[94:95] offset:16 nt
	global_load_dwordx4 v[246:249], v254, s[94:95] offset:32 nt
	global_load_dwordx4 v[250:253], v254, s[94:95] offset:48 nt
	v_readlane_b32 s98, v244, 24
	v_readlane_b32 s99, v244, 25
	s_nop 1
	s_add_u32 s94, s98, s32
	s_addc_u32 s95, s99, 0
	global_load_dwordx4 v[216:219], v254, s[94:95] nt
	global_load_dwordx4 v[220:223], v254, s[94:95] offset:16 nt
	global_load_dwordx4 v[224:227], v254, s[94:95] offset:32 nt
	global_load_dwordx4 v[228:231], v254, s[94:95] offset:48 nt

.LBB0_1424:
	v_lshl_add_u32 v2, s10, 2, v2
	v_add_u32_e32 v2, 0x8000, v2
	s_mov_b32 s0, 0x8000
	v_cmp_gt_i32_e32 vcc, s0, v2
	s_and_saveexec_b64 s[4:5], vcc
	s_cbranch_execz .LBB0_1429
	v_ashrrev_i32_e32 v3, 31, v2
	s_waitcnt vmcnt(6)
	v_and_b32_e32 v1, 63, v26
	v_lshlrev_b64 v[8:9], 9, v[2:3]
	v_readlane_b32 s16, v245, 7
	s_lshl_b32 s6, s2, 2
	v_lshl_or_b32 v8, v1, 3, v8
	v_readlane_b32 s18, v245, 9
	v_lshlrev_b32_e32 v4, 2, v1
	v_mov_b32_e32 v5, 0
	v_lshl_add_u64 v[6:7], v[2:3], 2, s[82:83]
	s_mov_b64 s[8:9], 0xa310800
	s_ashr_i32 s7, s6, 31
	v_lshl_add_u64 v[8:9], s[82:83], 0, v[8:9]
	s_mov_b64 s[12:13], 0x4280000
	v_readlane_b32 s17, v245, 8
	s_lshl_b32 s3, s18, 12
	v_cmp_eq_u32_e64 s[0:1], 0, v1
	v_lshl_add_u64 v[6:7], v[6:7], 0, s[8:9]
	s_lshl_b64 s[8:9], s[6:7], 2
	v_lshl_add_u64 v[8:9], v[8:9], 0, s[12:13]
	s_lshl_b64 s[12:13], s[6:7], 9
	v_lshlrev_b32_e32 v1, 10, v2
	s_add_i32 s3, s3, 0xfff80000
	s_mov_b64 s[16:17], 0
	v_mov_b32_e32 v3, s79
	v_mov_b32_e32 v12, s77
	v_mov_b32_e32 v13, s78
	v_mov_b32_e32 v14, s76
	v_lshlrev_b32_e32 v10, 4, v4
	v_mov_b32_e32 v11, v5
	s_mov_b32 s7, 0x40c00000
	s_movk_i32 s11, 0x7fff
	v_readlane_b32 s19, v245, 10
	s_branch .LBB0_1427
